# scan loop v2: o produced transposed by swapping MFMA operands (4 dwordx2 stores instead of 16 short stores per lane and step); u - w.S formed in the MFMA chain via a -identity selector fragment (2 dwo
# speedup vs baseline: 1.0092x; 1.0030x over previous
; #define LAS __attribute__((address_space(3)))
; __device__ __forceinline__ void gdn_scan_full(const bf16* CHUNK, const float* CD, bf16* OG, LAS unsigned char* lds, int item, int tid, int wave, int lane) {
;     ...
;     LAS bf16* Sb = (LAS bf16*)lds;
;     LAS bf16* Vn = Sb + 128 * 136;
;     for (int e = tid; e < 128 * 136 / 2; e += NTHR) ((LAS unsigned*)Sb)[e] = 0u;
;     f32x4 S[8];
; #pragma unroll
;     for (int t = 0; t < 8; ++t) S[t] = (f32x4){0.f, 0.f, 0.f, 0.f};
;     const int jb0 = ((d * 2 + b) * 16 + h) * 64;
;     bf16* og = OG + (size_t)d * M * 2048 + (size_t)b * SEQ * 2048 + h * 128 + 64 * ng + ql;
;     bf16x8_t wf[4], qf[4], inf[2], kf[2]; unsigned short uu[16]; float cdv;
;     bf16x8_t wfn[4], qfn[4], infn[2], kfn[2]; unsigned short uun[16]; float cdn;
;     ...
;     GF_LOAD(0, wfn, qfn, infn, kfn, uun, cdn);
;     __syncthreads();
.LBB0_365:
	v_add_u32_e32 v1, 0x200, v1
	s_movk_i32 s14, 0x1fff
	v_cmp_lt_u32_e32 vcc, s14, v1
	ds_write_b32 v0, v145
	s_or_b64 s[0:1], vcc, s[0:1]
	v_add_u32_e32 v0, 0x800, v0
	s_andn2_b64 exec, exec, s[0:1]
	s_cbranch_execnz .LBB0_365
	s_or_b64 exec, exec, s[0:1]
	s_bfe_u32 s42, s37, 0x10004
	s_and_b32 s0, s37, 0xffffffe0
	s_lshl_b32 s16, s42, 4
	s_or_b32 s0, s0, s16
	s_and_b32 s1, s36, 15
	s_or_b32 s17, s0, s1
	s_lshl_b32 s0, s17, 6
	s_ashr_i32 s1, s0, 31
	s_lshl_b64 s[14:15], s[0:1], 2
	s_add_u32 s38, s14, 0x43c00004
	s_addc_u32 s39, s15, 0
	s_mul_hi_i32 s40, s0, 0x12000
	v_mad_i64_i32 v[178:179], s[14:15], s0, v204, v[156:157]
	v_mad_i64_i32 v[180:181], s[14:15], s0, v204, v[158:159]
	v_mad_i64_i32 v[182:183], s[14:15], s0, v204, v[160:161]
	v_mad_i64_i32 v[184:185], s[14:15], s0, v204, v[162:163]
	v_mad_i64_i32 v[188:189], s[0:1], s0, v204, v[166:167]
	s_and_b32 s0, s37, 0x3ffffe0
	s_and_b32 s43, s37, 15
	s_or_b32 s0, s16, s0
	s_ashr_i32 s14, s37, 5
	s_or_b32 s16, s0, s43
	s_lshl_b32 s0, s16, 6
	s_ashr_i32 s15, s14, 31
	s_mul_i32 s17, s17, 0x480000
	s_lshl_b64 s[14:15], s[14:15], 25
	s_ashr_i32 s1, s0, 31
	s_mul_i32 s16, s16, 0x480000
	v_or_b32_e32 v186, s17, v164
	v_or_b32_e32 v190, s17, v168
	s_mul_hi_i32 s17, s0, 0x12000
	s_add_u32 s16, s33, s16
	s_addc_u32 s17, s82, s17
	v_mov_b32_e32 v171, v145
	v_mov_b32_e32 v173, v145
	v_lshl_add_u64 v[0:1], s[16:17], 0, v[170:171]
	v_mov_b32_e32 v187, s40
	v_mov_b32_e32 v191, s40
	v_lshl_add_u64 v[0:1], v[0:1], 0, v[172:173]
	s_mov_b64 s[40:41], 0x4000
	v_lshl_add_u64 v[2:3], v[0:1], 0, s[40:41]
	s_mov_b64 s[40:41], 0x8000
	v_lshl_add_u64 v[4:5], v[0:1], 0, s[40:41]
	s_movk_i32 s40, 0x4000
	v_add_co_u32_e32 v6, vcc, s40, v0
	v_readlane_b32 s44, v253, 32
	s_nop 0
	v_addc_co_u32_e32 v7, vcc, 0, v1, vcc
	s_mov_b32 s41, 0x8000
	v_readlane_b32 s45, v253, 33
	s_add_u32 s14, s44, s14
	v_add_co_u32_e32 v0, vcc, s41, v0
	s_addc_u32 s15, s45, s15
	s_lshl_b32 s41, s42, 24
	v_addc_co_u32_e32 v1, vcc, 0, v1, vcc
	s_add_u32 s14, s14, s41
	v_mov_b32_e32 v175, v145
	global_load_dwordx4 v[24:27], v[6:7], off
	global_load_dwordx4 v[16:19], v[0:1], off
	global_load_dwordx4 v[28:31], v[2:3], off offset:64
	global_load_dwordx4 v[12:15], v[4:5], off offset:64
	global_load_dwordx4 v[36:39], v[2:3], off offset:128
	global_load_dwordx4 v[8:11], v[4:5], off offset:128
	global_load_dwordx4 v[32:35], v[2:3], off offset:192
	global_load_dwordx4 v[20:23], v[4:5], off offset:192
	s_addc_u32 s15, s15, 0
	s_lshl_b32 s41, s43, 8
	v_lshl_add_u64 v[0:1], s[16:17], 0, v[174:175]
	s_add_u32 s14, s14, s41
	v_lshl_add_u64 v[0:1], v[0:1], 0, v[172:173]
	s_mov_b64 s[42:43], 0x10000
	s_mov_b32 s41, 0x10000
	v_lshl_add_u64 v[2:3], v[0:1], 0, s[42:43]
	v_lshl_add_u64 v[4:5], v[146:147], 1, s[16:17]
	v_add_co_u32_e32 v0, vcc, s41, v0
	s_addc_u32 s15, s15, 0
	v_lshl_add_u64 v[4:5], v[4:5], 0, v[172:173]
	v_addc_co_u32_e32 v1, vcc, 0, v1, vcc
	s_add_u32 s14, s14, s18
	s_mov_b64 s[42:43], 0xc000
	global_load_dwordx4 v[40:43], v[0:1], off
	v_add_co_u32_e32 v0, vcc, s19, v4
	s_addc_u32 s15, s15, 0
	v_lshl_add_u64 v[48:49], v[4:5], 0, s[42:43]
	v_addc_co_u32_e32 v1, vcc, 0, v5, vcc
	v_mov_b32_e32 v177, v145
	global_load_dwordx4 v[4:7], v[0:1], off
	global_load_dwordx4 v[44:47], v[2:3], off offset:64
	s_nop 0
	global_load_dwordx4 v[0:3], v[48:49], off offset:64
	v_lshl_add_u64 v[48:49], v[148:149], 1, s[16:17]
	v_lshl_add_u64 v[50:51], v[150:151], 1, s[16:17]
	v_lshl_add_u64 v[192:193], s[14:15], 0, v[176:177]
	s_lshl_b64 s[0:1], s[0:1], 2
	v_readlane_b32 s14, v253, 40
	global_load_ushort v175, v[48:49], off
	global_load_ushort v52, v[48:49], off offset:256
	global_load_ushort v53, v[48:49], off offset:512
	global_load_ushort v173, v[48:49], off offset:768
	global_load_ushort v171, v[48:49], off offset:32
	global_load_ushort v54, v[50:51], off offset:256
	global_load_ushort v55, v[50:51], off offset:512
	global_load_ushort v214, v[50:51], off offset:768
	global_load_ushort v213, v[48:49], off offset:64
	v_lshl_add_u64 v[50:51], v[152:153], 1, s[16:17]
	s_add_u32 s0, s14, s0
	v_readlane_b32 s14, v253, 41
	global_load_ushort v56, v[50:51], off offset:256
	global_load_ushort v57, v[50:51], off offset:512
	global_load_ushort v216, v[50:51], off offset:768
	global_load_ushort v215, v[48:49], off offset:96
	v_lshl_add_u64 v[48:49], v[154:155], 1, s[16:17]
	s_addc_u32 s1, s14, s1
	global_load_ushort v50, v[48:49], off offset:256
	global_load_ushort v51, v[48:49], off offset:512
	global_load_ushort v217, v[48:49], off offset:768
	global_load_dword v194, v145, s[0:1]
	s_cmp_lt_u32 s37, 32
	v_mov_b32_e32 v48, 0
	s_mov_b32 s40, 0
	s_cselect_b64 vcc, -1, 0
	v_mov_b32_e32 v177, v203
	v_mov_b32_e32 v49, v48
	v_mov_b32_e32 v58, v48
	v_mov_b32_e32 v59, v48
	v_mov_b32_e32 v60, v48
	v_mov_b32_e32 v61, v48
	v_mov_b32_e32 v62, v48
	v_mov_b32_e32 v63, v48
	v_mov_b32_e32 v64, v48
	v_mov_b32_e32 v65, v48
	v_mov_b32_e32 v66, v48
	v_mov_b32_e32 v67, v48
	v_mov_b32_e32 v68, v48
	v_mov_b32_e32 v69, v48
	v_mov_b32_e32 v70, v48
	v_mov_b32_e32 v71, v48
	v_mov_b32_e32 v76, v48
	v_mov_b32_e32 v77, v48
	v_mov_b32_e32 v78, v48
	v_mov_b32_e32 v79, v48
	v_mov_b32_e32 v72, v48
	v_mov_b32_e32 v73, v48
	v_mov_b32_e32 v74, v48
	v_mov_b32_e32 v75, v48
	s_waitcnt lgkmcnt(0)
	s_barrier
; #define LAS __attribute__((address_space(3)))
; __device__ __forceinline__ unsigned f2bf(float f) { return pk2(f, f) & 0xffffu; }
; __device__ __forceinline__ void gdn_scan_full(const bf16* CHUNK, const float* CD, bf16* OG, LAS unsigned char* lds, int item, int tid, int wave, int lane) {
;     ...
;     for (int n = 0; n < 64; ++n) {
; #pragma unroll
;         for (int s = 0; s < 4; ++s) { wf[s] = wfn[s]; qf[s] = qfn[s]; }
; #pragma unroll
;         for (int s = 0; s < 2; ++s) { inf[s] = infn[s]; kf[s] = kfn[s]; }
; #pragma unroll
;         for (int j = 0; j < 16; ++j) uu[j] = uun[j];
;         cdv = cdn;
;         if (n + 1 < 64) GF_LOAD(n + 1, wfn, qfn, infn, kfn, uun, cdn);
;         f32x4 wsum[4], os[4];
; #pragma unroll
;         for (int t = 0; t < 4; ++t) { wsum[t] = (f32x4){0.f, 0.f, 0.f, 0.f}; os[t] = (f32x4){0.f, 0.f, 0.f, 0.f}; }
; #pragma unroll
;         for (int t = 0; t < 4; ++t)
; #pragma unroll
;             for (int s = 0; s < 4; ++s) { const bf16x8_t sf = *(const LAS bf16x8_t*)(Sb + (64 * ng + 16 * t + ql) * 136 + 32 * s + 8 * gq);
;                 wsum[t] = __builtin_amdgcn_mfma_f32_16x16x32_bf16(wf[s], sf, wsum[t], 0, 0, 0); os[t] = __builtin_amdgcn_mfma_f32_16x16x32_bf16(qf[s], sf, os[t], 0, 0, 0); }
; #pragma unroll
;         for (int t = 0; t < 4; ++t) { s16x4_t vn;
; #pragma unroll
;             for (int j = 0; j < 4; ++j) vn[j] = (short)f2bf(__uint_as_float((unsigned)uu[t * 4 + j] << 16) - wsum[t][j]);
;             *(LAS s16x4_t*)(Vn + (64 * ng + 16 * t + ql) * 72 + 16 * mt + 4 * gq) = vn; }
	s_waitcnt vmcnt(14)
	v_perm_b32 v228, v53, v52, s20
	s_waitcnt vmcnt(10)
	v_perm_b32 v227, v55, v54, s20
	v_mov_b32_e32 v52, v48
	v_mov_b32_e32 v53, v48
	v_mov_b32_e32 v54, v48
	s_waitcnt vmcnt(6)
	v_perm_b32 v226, v57, v56, s20
	v_mov_b32_e32 v55, v48
	v_mov_b32_e32 v56, v48
	v_mov_b32_e32 v57, v48
	s_waitcnt vmcnt(2)
	v_perm_b32 v144, v51, v50, s20
	v_mov_b32_e32 v50, v48
	v_mov_b32_e32 v51, v48
	s_waitcnt vmcnt(0)
	v_mbcnt_lo_u32_b32 v196, -1, 0
	v_mbcnt_hi_u32_b32 v196, -1, v196
	v_and_b32_e32 v250, 15, v196
	v_lshrrev_b32_e32 v251, 4, v196
	v_lshrrev_b32_e32 v252, 3, v250
	v_and_b32_e32 v97, 7, v250
	v_lshrrev_b32_e32 v109, 1, v97
	v_and_b32_e32 v97, 1, v97
	v_lshlrev_b32_e32 v97, 4, v97
	v_mov_b32_e32 v213, 0xbf80
	v_lshlrev_b32_e32 v213, v97, v213
	v_xor_b32_e32 v252, v251, v252
	v_xor_b32_e32 v251, 2, v252
	v_xor_b32_e32 v97, 0, v109
	v_or_b32_e32 v97, v97, v252
	v_cmp_eq_u32_e64 s[0:1], 0, v97
	s_nop 1
	v_cndmask_b32_e64 v222, 0, v213, s[0:1]
	v_xor_b32_e32 v97, 1, v109
	v_or_b32_e32 v97, v97, v252
	v_cmp_eq_u32_e64 s[0:1], 0, v97
	s_nop 1
	v_cndmask_b32_e64 v223, 0, v213, s[0:1]
	v_xor_b32_e32 v97, 2, v109
	v_or_b32_e32 v97, v97, v252
	v_cmp_eq_u32_e64 s[0:1], 0, v97
	s_nop 1
	v_cndmask_b32_e64 v224, 0, v213, s[0:1]
	v_xor_b32_e32 v97, 3, v109
	v_or_b32_e32 v97, v97, v252
	v_cmp_eq_u32_e64 s[0:1], 0, v97
	s_nop 1
	v_cndmask_b32_e64 v225, 0, v213, s[0:1]
	v_xor_b32_e32 v97, 0, v109
	v_or_b32_e32 v97, v97, v251
	v_cmp_eq_u32_e64 s[0:1], 0, v97
	s_nop 1
	v_cndmask_b32_e64 v226, 0, v213, s[0:1]
	v_xor_b32_e32 v97, 1, v109
	v_or_b32_e32 v97, v97, v251
	v_cmp_eq_u32_e64 s[0:1], 0, v97
	s_nop 1
	v_cndmask_b32_e64 v227, 0, v213, s[0:1]
	v_xor_b32_e32 v97, 2, v109
	v_or_b32_e32 v97, v97, v251
	v_cmp_eq_u32_e64 s[0:1], 0, v97
	s_nop 1
	v_cndmask_b32_e64 v228, 0, v213, s[0:1]
	v_xor_b32_e32 v97, 3, v109
	v_or_b32_e32 v97, v97, v251
	v_cmp_eq_u32_e64 s[0:1], 0, v97
	s_nop 1
	v_cndmask_b32_e64 v229, 0, v213, s[0:1]
	s_lshr_b32 s98, s78, 2
	s_lshl_b32 s98, s98, 7
	s_add_u32 s98, s98, s35
	s_add_u32 s0, s28, s98
	s_addc_u32 s1, s29, 0
	s_sub_u32 s0, s0, s12
	s_subb_u32 s1, s1, s13
	v_lshl_add_u64 v[246:247], s[0:1], 0, v[186:187]
	global_load_dwordx4 v[214:217], v[246:247], off
	global_load_dwordx4 v[218:221], v[246:247], off offset:64
	s_waitcnt vmcnt(0)
.LBB0_367:
	v_add_u32_e32 v108, v195, v197
	v_add_u32_e32 v104, v195, v198
	v_add_u32_e32 v105, v169, v197
	v_add_u32_e32 v96, v169, v198
	ds_read_b128 v[80:83], v205
	ds_read_b128 v[84:87], v205 offset:64
	ds_read_b128 v[88:91], v205 offset:128
	ds_read_b128 v[92:95], v205 offset:192
	ds_read_b128 v[100:103], v205 offset:4352
	ds_read_b128 v[112:115], v205 offset:4416
	ds_read_b128 v[116:119], v205 offset:4480
	ds_read_b128 v[120:123], v205 offset:4544
	s_waitcnt lgkmcnt(7)
	v_mfma_f32_16x16x32_bf16 v[124:127], v[24:27], v[80:83], 0
	v_mul_f32_e32 v72, v194, v72
	v_mfma_f32_16x16x32_bf16 v[230:233], v[80:83], v[16:19], 0
	v_mul_f32_e32 v73, v194, v73
	ds_read_b128 v[80:83], v205 offset:8704
	s_waitcnt lgkmcnt(7)
	v_mfma_f32_16x16x32_bf16 v[124:127], v[28:31], v[84:87], v[124:127]
	v_mul_f32_e32 v74, v194, v74
	v_mfma_f32_16x16x32_bf16 v[230:233], v[84:87], v[12:15], v[230:233]
	v_mul_f32_e32 v75, v194, v75
	ds_read_b128 v[84:87], v205 offset:8768
	s_waitcnt lgkmcnt(7)
	v_mfma_f32_16x16x32_bf16 v[124:127], v[36:39], v[88:91], v[124:127]
	v_mul_f32_e32 v76, v194, v76
	v_mfma_f32_16x16x32_bf16 v[230:233], v[88:91], v[8:11], v[230:233]
	v_mul_f32_e32 v77, v194, v77
	ds_read_b128 v[88:91], v205 offset:8832
	s_waitcnt lgkmcnt(7)
	v_mfma_f32_16x16x32_bf16 v[124:127], v[32:35], v[92:95], v[124:127]
	v_mul_f32_e32 v78, v194, v78
	v_mfma_f32_16x16x32_bf16 v[230:233], v[92:95], v[20:23], v[230:233]
	v_mul_f32_e32 v79, v194, v79
	ds_read_b128 v[92:95], v205 offset:8896
	v_mfma_f32_16x16x32_bf16 v[124:127], v[214:217], v[222:225], v[124:127]
	s_waitcnt lgkmcnt(7)
	v_mfma_f32_16x16x32_bf16 v[128:131], v[24:27], v[100:103], 0
	v_mul_f32_e32 v68, v194, v68
	v_mfma_f32_16x16x32_bf16 v[234:237], v[100:103], v[16:19], 0
	v_mul_f32_e32 v69, v194, v69
	ds_read_b128 v[100:103], v206
	s_nop 1
	v_cvt_pk_bf16_f32 v98, -v124, -v125
	v_cvt_pk_bf16_f32 v99, -v126, -v127
	s_waitcnt lgkmcnt(7)
	v_mfma_f32_16x16x32_bf16 v[128:131], v[28:31], v[112:115], v[128:131]
	v_mul_f32_e32 v70, v194, v70
	v_mfma_f32_16x16x32_bf16 v[234:237], v[112:115], v[12:15], v[234:237]
	v_mul_f32_e32 v71, v194, v71
	ds_read_b128 v[112:115], v206 offset:64
	ds_write_b64 v108, v[98:99] offset:34816
	s_waitcnt lgkmcnt(8)
	v_mfma_f32_16x16x32_bf16 v[128:131], v[36:39], v[116:119], v[128:131]
	v_mul_f32_e32 v64, v194, v64
	v_mfma_f32_16x16x32_bf16 v[234:237], v[116:119], v[8:11], v[234:237]
	v_mul_f32_e32 v65, v194, v65
	ds_read_b128 v[116:119], v206 offset:128
	s_waitcnt lgkmcnt(8)
	v_mfma_f32_16x16x32_bf16 v[128:131], v[32:35], v[120:123], v[128:131]
	v_mul_f32_e32 v66, v194, v66
	v_mfma_f32_16x16x32_bf16 v[234:237], v[120:123], v[20:23], v[234:237]
	v_mul_f32_e32 v67, v194, v67
	ds_read_b128 v[120:123], v206 offset:192
	v_mfma_f32_16x16x32_bf16 v[128:131], v[214:217], v[226:229], v[128:131]
	s_waitcnt lgkmcnt(8)
	v_mfma_f32_16x16x32_bf16 v[132:135], v[24:27], v[80:83], 0
	v_mul_f32_e32 v60, v194, v60
	v_mfma_f32_16x16x32_bf16 v[238:241], v[80:83], v[16:19], 0
	v_mul_f32_e32 v61, v194, v61
	s_nop 2
	v_cvt_pk_bf16_f32 v106, -v128, -v129
	v_cvt_pk_bf16_f32 v107, -v130, -v131
	s_waitcnt lgkmcnt(7)
	v_mfma_f32_16x16x32_bf16 v[132:135], v[28:31], v[84:87], v[132:135]
	v_mul_f32_e32 v62, v194, v62
	v_mfma_f32_16x16x32_bf16 v[238:241], v[84:87], v[12:15], v[238:241]
	v_mul_f32_e32 v63, v194, v63
	ds_write_b64 v108, v[106:107] offset:37120
	s_waitcnt lgkmcnt(7)
; #define LAS __attribute__((address_space(3)))
; #define LDS_BARRIER() do { asm volatile("s_waitcnt lgkmcnt(0)" ::: "memory"); __builtin_amdgcn_s_barrier(); asm volatile("" ::: "memory"); } while (0)
; __device__ __forceinline__ unsigned f2bf(float f) { return pk2(f, f) & 0xffffu; }
; __device__ __forceinline__ void gdn_scan_full(const bf16* CHUNK, const float* CD, bf16* OG, LAS unsigned char* lds, int item, int tid, int wave, int lane) {
;     ...
;     GF_LOAD(0, wfn, qfn, infn, kfn, uun, cdn);
;     __syncthreads();
;     for (int n = 0; n < 64; ++n) {
; #pragma unroll
;         for (int s = 0; s < 4; ++s) { wf[s] = wfn[s]; qf[s] = qfn[s]; }
; #pragma unroll
;         for (int s = 0; s < 2; ++s) { inf[s] = infn[s]; kf[s] = kfn[s]; }
; #pragma unroll
;         for (int j = 0; j < 16; ++j) uu[j] = uun[j];
;         cdv = cdn;
;         if (n + 1 < 64) GF_LOAD(n + 1, wfn, qfn, infn, kfn, uun, cdn);
;         f32x4 wsum[4], os[4];
; #pragma unroll
;         for (int t = 0; t < 4; ++t) { wsum[t] = (f32x4){0.f, 0.f, 0.f, 0.f}; os[t] = (f32x4){0.f, 0.f, 0.f, 0.f}; }
; #pragma unroll
;         for (int t = 0; t < 4; ++t)
; #pragma unroll
;             for (int s = 0; s < 4; ++s) { const bf16x8_t sf = *(const LAS bf16x8_t*)(Sb + (64 * ng + 16 * t + ql) * 136 + 32 * s + 8 * gq);
;                 wsum[t] = __builtin_amdgcn_mfma_f32_16x16x32_bf16(wf[s], sf, wsum[t], 0, 0, 0); os[t] = __builtin_amdgcn_mfma_f32_16x16x32_bf16(qf[s], sf, os[t], 0, 0, 0); }
; #pragma unroll
;         for (int t = 0; t < 4; ++t) { s16x4_t vn;
; #pragma unroll
;             for (int j = 0; j < 4; ++j) vn[j] = (short)f2bf(__uint_as_float((unsigned)uu[t * 4 + j] << 16) - wsum[t][j]);
;             *(LAS s16x4_t*)(Vn + (64 * ng + 16 * t + ql) * 72 + 16 * mt + 4 * gq) = vn; }
;         LDS_BARRIER();
; #pragma unroll
;         for (int t = 0; t < 4; ++t)
; #pragma unroll
;             for (int s = 0; s < 2; ++s) { const bf16x8_t vf = *(const LAS bf16x8_t*)(Vn + (64 * ng + 16 * t + ql) * 72 + 32 * s + 8 * gq); os[t] = __builtin_amdgcn_mfma_f32_16x16x32_bf16(inf[s], vf, os[t], 0, 0, 0); }
; #pragma unroll
;         for (int j = 0; j < 4; ++j) { const int c = n * 64 + 16 * mt + 4 * gq + j; const int tok = d ? SEQ - 1 - c : c;
; #pragma unroll
;             for (int t = 0; t < 4; ++t) og[(size_t)tok * 2048 + 16 * t] = (bf16)f2bf(os[t][j]); }
	v_mfma_f32_16x16x32_bf16 v[132:135], v[36:39], v[88:91], v[132:135]
	v_mul_f32_e32 v56, v194, v56
	v_mfma_f32_16x16x32_bf16 v[238:241], v[88:91], v[8:11], v[238:241]
	v_mul_f32_e32 v57, v194, v57
	s_waitcnt lgkmcnt(6)
	v_mfma_f32_16x16x32_bf16 v[132:135], v[32:35], v[92:95], v[132:135]
	v_mul_f32_e32 v58, v194, v58
	v_mfma_f32_16x16x32_bf16 v[238:241], v[92:95], v[20:23], v[238:241]
	v_mul_f32_e32 v59, v194, v59
	v_mfma_f32_16x16x32_bf16 v[132:135], v[218:221], v[222:225], v[132:135]
	s_waitcnt lgkmcnt(5)
	v_mfma_f32_16x16x32_bf16 v[136:139], v[24:27], v[100:103], 0
	v_mul_f32_e32 v52, v194, v52
	v_mfma_f32_16x16x32_bf16 v[242:245], v[100:103], v[16:19], 0
	v_mul_f32_e32 v53, v194, v53
	s_nop 2
	v_cvt_pk_bf16_f32 v110, -v132, -v133
	v_cvt_pk_bf16_f32 v111, -v134, -v135
	s_waitcnt lgkmcnt(4)
	v_mfma_f32_16x16x32_bf16 v[136:139], v[28:31], v[112:115], v[136:139]
	v_mul_f32_e32 v54, v194, v54
	v_mfma_f32_16x16x32_bf16 v[242:245], v[112:115], v[12:15], v[242:245]
	v_mul_f32_e32 v55, v194, v55
	ds_write_b64 v108, v[110:111] offset:39424
	s_waitcnt lgkmcnt(3)
	v_mfma_f32_16x16x32_bf16 v[136:139], v[36:39], v[116:119], v[136:139]
	v_mul_f32_e32 v48, v194, v48
	v_mfma_f32_16x16x32_bf16 v[242:245], v[116:119], v[8:11], v[242:245]
	v_mul_f32_e32 v49, v194, v49
	s_waitcnt lgkmcnt(2)
	v_mfma_f32_16x16x32_bf16 v[136:139], v[32:35], v[120:123], v[136:139]
	v_mul_f32_e32 v50, v194, v50
	v_mfma_f32_16x16x32_bf16 v[242:245], v[120:123], v[20:23], v[242:245]
	v_mul_f32_e32 v51, v194, v51
	v_mfma_f32_16x16x32_bf16 v[136:139], v[218:221], v[226:229], v[136:139]
	s_add_u32 s0, s28, s21
	s_addc_u32 s1, s29, 0
	v_lshl_add_u64 v[246:247], s[0:1], 0, v[186:187]
	s_add_u32 s0, s28, s22
	s_addc_u32 s1, s29, 0
	v_lshl_add_u64 v[248:249], s[0:1], 0, v[186:187]
	s_nop 1
	v_cvt_pk_bf16_f32 v98, -v136, -v137
	v_cvt_pk_bf16_f32 v99, -v138, -v139
	ds_write_b64 v104, v[98:99] offset:34816
	global_load_dwordx4 v[24:27], v[246:247], off
	global_load_dwordx4 v[16:19], v[248:249], off
	global_load_dwordx4 v[28:31], v[246:247], off offset:64
	global_load_dwordx4 v[12:15], v[248:249], off offset:64
	global_load_dwordx4 v[36:39], v[246:247], off offset:128
	global_load_dwordx4 v[8:11], v[248:249], off offset:128
	global_load_dwordx4 v[32:35], v[246:247], off offset:192
	global_load_dwordx4 v[20:23], v[248:249], off offset:192
	s_add_u32 s0, s28, s98
	s_addc_u32 s1, s29, 0
	v_lshl_add_u64 v[246:247], s[0:1], 0, v[186:187]
	global_load_dwordx4 v[214:217], v[246:247], off
	global_load_dwordx4 v[218:221], v[246:247], off offset:64
	s_add_u32 s0, s28, s38
	s_addc_u32 s1, s29, s39
	s_nop 0
	global_load_dword v194, v145, s[0:1]
	s_add_u32 s38, s38, 4
	s_addc_u32 s39, s39, 0
	s_waitcnt lgkmcnt(0)
	s_barrier
	ds_read_b128 v[80:83], v105 offset:34816
	ds_read_b128 v[84:87], v105 offset:34880
	ds_read_b128 v[88:91], v105 offset:37120
	ds_read_b128 v[92:95], v105 offset:37184
	ds_read_b128 v[100:103], v105 offset:39424
	ds_read_b128 v[112:115], v105 offset:39488
	ds_read_b128 v[116:119], v96 offset:34816
	ds_read_b128 v[120:123], v96 offset:34880
	ds_read_b128 v[124:127], v207 offset:34816
	ds_read_b128 v[128:131], v207 offset:34880
	ds_read_b128 v[132:135], v207 offset:37120
	ds_read_b128 v[136:139], v207 offset:37184
	ds_read_b128 v[246:249], v207 offset:39424
	s_waitcnt vmcnt(17)
	s_waitcnt lgkmcnt(12)
	v_mfma_f32_16x16x32_bf16 v[230:233], v[80:83], v[40:43], v[230:233]
	ds_read_b128 v[80:83], v207 offset:39488
	s_waitcnt lgkmcnt(12)
	v_mfma_f32_16x16x32_bf16 v[230:233], v[84:87], v[44:47], v[230:233]
	ds_read_b128 v[84:87], v208 offset:34816
	s_waitcnt lgkmcnt(12)
	v_mfma_f32_16x16x32_bf16 v[234:237], v[88:91], v[40:43], v[234:237]
	ds_read_b128 v[88:91], v208 offset:34880
	s_waitcnt lgkmcnt(12)
	v_mfma_f32_16x16x32_bf16 v[234:237], v[92:95], v[44:47], v[234:237]
	ds_read_b128 v[92:95], v207 offset:44032
	s_waitcnt lgkmcnt(12)
	v_mfma_f32_16x16x32_bf16 v[238:241], v[100:103], v[40:43], v[238:241]
	ds_read_b128 v[100:103], v207 offset:44096
	s_waitcnt lgkmcnt(12)
	v_mfma_f32_16x16x32_bf16 v[238:241], v[112:115], v[44:47], v[238:241]
	ds_read_b128 v[112:115], v207 offset:46336
	s_waitcnt lgkmcnt(12)
	v_mfma_f32_16x16x32_bf16 v[242:245], v[116:119], v[40:43], v[242:245]
	ds_read_b128 v[116:119], v207 offset:46400
	s_waitcnt lgkmcnt(12)
	v_mfma_f32_16x16x32_bf16 v[242:245], v[120:123], v[44:47], v[242:245]
	ds_read_b128 v[120:123], v207 offset:48640
	s_add_u32 s0, s28, s23
	s_addc_u32 s1, s29, 0
	v_lshl_add_u64 v[110:111], s[0:1], 0, v[190:191]
	global_load_dwordx4 v[40:43], v[110:111], off
	global_load_dwordx4 v[44:47], v[110:111], off offset:64
	v_mbcnt_lo_u32_b32 v196, -1, 0
	v_mbcnt_hi_u32_b32 v196, -1, v196
	v_and_b32_e32 v250, 15, v196
	v_lshrrev_b32_e32 v251, 2, v196
	v_and_b32_e32 v251, 12, v251
	v_sub_u32_e32 v251, v251, v250
	v_add_u32_e32 v252, s40, v141
	v_sub_u32_e32 v252, v252, v251
	v_add3_u32 v97, v177, v251, 3
	v_cndmask_b32_e32 v97, v97, v252, vcc
	v_lshlrev_b32_e32 v97, 12, v97
	v_lshl_add_u32 v109, v251, 1, v97
	v_add_u32_e32 v144, 64, v109
	v_lshl_add_u64 v[98:99], v[192:193], 0, v[144:145]
	v_cvt_pk_bf16_f32 v106, v230, v231
	v_cvt_pk_bf16_f32 v107, v232, v233
	global_store_dwordx2 v[98:99], v[106:107], off offset:-64
	v_cvt_pk_bf16_f32 v110, v234, v235
	v_cvt_pk_bf16_f32 v111, v236, v237
	global_store_dwordx2 v[98:99], v[110:111], off offset:-32
	v_cvt_pk_bf16_f32 v106, v238, v239
	v_cvt_pk_bf16_f32 v107, v240, v241
	global_store_dwordx2 v[98:99], v[106:107], off offset:0
	v_cvt_pk_bf16_f32 v110, v242, v243
	v_cvt_pk_bf16_f32 v111, v244, v245
	global_store_dwordx2 v[98:99], v[110:111], off offset:32
	ds_read_b128 v[230:233], v207 offset:48704
	ds_read_b128 v[234:237], v209 offset:34816
	ds_read_b128 v[238:241], v209 offset:34880
	s_add_i32 s40, s40, 64
	v_subrev_u32_e32 v177, 64, v177
	s_waitcnt vmcnt(17)
; #define LAS __attribute__((address_space(3)))
; #define LDS_BARRIER() do { asm volatile("s_waitcnt lgkmcnt(0)" ::: "memory"); __builtin_amdgcn_s_barrier(); asm volatile("" ::: "memory"); } while (0)
; __device__ __forceinline__ unsigned f2bf(float f) { return pk2(f, f) & 0xffffu; }
; __device__ __forceinline__ void gdn_scan_full(const bf16* CHUNK, const float* CD, bf16* OG, LAS unsigned char* lds, int item, int tid, int wave, int lane) {
;     ...
;         for (int t = 0; t < 8; ++t) S[t] = S[t] * cdv;
; #pragma unroll
;         for (int t = 0; t < 8; ++t)
; #pragma unroll
;             for (int s = 0; s < 2; ++s) { const bf16x8_t v0 = *(const LAS bf16x8_t*)(Vn + (16 * t + ql) * 72 + 32 * s + 8 * gq); S[t] = __builtin_amdgcn_mfma_f32_16x16x32_bf16(kf[s], v0, S[t], 0, 0, 0); }
; #pragma unroll
;         for (int t = 0; t < 8; ++t) { s16x4_t p;
; #pragma unroll
;             for (int j = 0; j < 4; ++j) p[j] = (short)f2bf(S[t][j]);
;             *(LAS s16x4_t*)(Sb + (16 * t + ql) * 136 + 16 * wave + 4 * gq) = p; }
;         LDS_BARRIER();
	s_waitcnt lgkmcnt(15)
	v_mfma_f32_16x16x32_bf16 v[72:75], v[4:7], v[124:127], v[72:75]
	s_waitcnt lgkmcnt(14)
	v_mfma_f32_16x16x32_bf16 v[72:75], v[0:3], v[128:131], v[72:75]
	s_waitcnt lgkmcnt(13)
	v_mfma_f32_16x16x32_bf16 v[76:79], v[4:7], v[132:135], v[76:79]
	s_waitcnt lgkmcnt(12)
	v_mfma_f32_16x16x32_bf16 v[76:79], v[0:3], v[136:139], v[76:79]
	s_waitcnt lgkmcnt(11)
	v_mfma_f32_16x16x32_bf16 v[68:71], v[4:7], v[246:249], v[68:71]
	s_waitcnt lgkmcnt(10)
	v_mfma_f32_16x16x32_bf16 v[68:71], v[0:3], v[80:83], v[68:71]
	s_waitcnt lgkmcnt(9)
	v_mfma_f32_16x16x32_bf16 v[64:67], v[4:7], v[84:87], v[64:67]
	s_waitcnt lgkmcnt(8)
	v_mfma_f32_16x16x32_bf16 v[64:67], v[0:3], v[88:91], v[64:67]
	s_waitcnt lgkmcnt(7)
	v_mfma_f32_16x16x32_bf16 v[60:63], v[4:7], v[92:95], v[60:63]
	s_waitcnt lgkmcnt(6)
	v_mfma_f32_16x16x32_bf16 v[60:63], v[0:3], v[100:103], v[60:63]
	s_waitcnt lgkmcnt(5)
	v_mfma_f32_16x16x32_bf16 v[56:59], v[4:7], v[112:115], v[56:59]
	s_waitcnt lgkmcnt(4)
	v_mfma_f32_16x16x32_bf16 v[56:59], v[0:3], v[116:119], v[56:59]
	s_waitcnt lgkmcnt(3)
	v_mfma_f32_16x16x32_bf16 v[52:55], v[4:7], v[120:123], v[52:55]
	s_waitcnt lgkmcnt(2)
	v_mfma_f32_16x16x32_bf16 v[52:55], v[0:3], v[230:233], v[52:55]
	s_waitcnt lgkmcnt(1)
	v_mfma_f32_16x16x32_bf16 v[48:51], v[4:7], v[234:237], v[48:51]
	s_waitcnt lgkmcnt(0)
	v_mfma_f32_16x16x32_bf16 v[48:51], v[0:3], v[238:241], v[48:51]
	s_add_u32 s0, s28, s34
	s_addc_u32 s1, s29, 0
	v_lshl_add_u64 v[250:251], s[0:1], 0, v[188:189]
	global_load_dwordx4 v[4:7], v[250:251], off
	global_load_dwordx4 v[0:3], v[250:251], off offset:64
	v_lshl_add_u64 v[178:179], v[178:179], 0, s[12:13]
	v_lshl_add_u64 v[180:181], v[180:181], 0, s[12:13]
	v_lshl_add_u64 v[182:183], v[182:183], 0, s[12:13]
	v_lshl_add_u64 v[184:185], v[184:185], 0, s[12:13]
	v_lshl_add_u64 v[186:187], v[186:187], 0, s[12:13]
	v_lshl_add_u64 v[188:189], v[188:189], 0, s[12:13]
	v_lshl_add_u64 v[190:191], v[190:191], 0, s[12:13]
	v_cvt_pk_bf16_f32 v98, v72, v73
	v_cvt_pk_bf16_f32 v99, v74, v75
	ds_write_b64 v210, v[98:99]
	v_cvt_pk_bf16_f32 v106, v76, v77
	v_cvt_pk_bf16_f32 v107, v78, v79
	ds_write_b64 v210, v[106:107] offset:4352
	v_cvt_pk_bf16_f32 v98, v68, v69
	v_cvt_pk_bf16_f32 v99, v70, v71
	ds_write_b64 v210, v[98:99] offset:8704
	v_cvt_pk_bf16_f32 v106, v64, v65
	v_cvt_pk_bf16_f32 v107, v66, v67
	ds_write_b64 v211, v[106:107]
	v_cvt_pk_bf16_f32 v98, v60, v61
	v_cvt_pk_bf16_f32 v99, v62, v63
	ds_write_b64 v210, v[98:99] offset:17408
	v_cvt_pk_bf16_f32 v106, v56, v57
	v_cvt_pk_bf16_f32 v107, v58, v59
	ds_write_b64 v210, v[106:107] offset:21760
	v_cvt_pk_bf16_f32 v98, v52, v53
	v_cvt_pk_bf16_f32 v99, v54, v55
	ds_write_b64 v210, v[98:99] offset:26112
	v_cvt_pk_bf16_f32 v106, v48, v49
	v_cvt_pk_bf16_f32 v107, v50, v51
	ds_write_b64 v212, v[106:107]
	s_waitcnt vmcnt(8)
	s_cmpk_lg_i32 s40, 0xfc0
	s_waitcnt lgkmcnt(0)
	s_barrier
	s_cbranch_scc1 .LBB0_367
	s_waitcnt vmcnt(0)
	s_add_u32 s0, s28, s35
	s_addc_u32 s1, s29, 0
	s_sub_u32 s0, s0, s12
	s_subb_u32 s1, s1, s13
	v_lshl_add_u64 v[246:247], s[0:1], 0, v[184:185]
	v_lshl_add_u64 v[248:249], s[0:1], 0, v[182:183]
	v_lshl_add_u64 v[98:99], s[0:1], 0, v[180:181]
	v_lshl_add_u64 v[106:107], s[0:1], 0, v[178:179]
	global_load_ushort v175, v[246:247], off
	global_load_ushort v219, v[246:247], off offset:256
	global_load_ushort v218, v[246:247], off offset:512
	global_load_ushort v173, v[246:247], off offset:768
	global_load_ushort v171, v[246:247], off offset:32
	global_load_ushort v221, v[248:249], off offset:256
	global_load_ushort v220, v[248:249], off offset:512
	global_load_ushort v214, v[248:249], off offset:768
	global_load_ushort v213, v[246:247], off offset:64
	global_load_ushort v223, v[98:99], off offset:256
	global_load_ushort v222, v[98:99], off offset:512
	global_load_ushort v216, v[98:99], off offset:768
	global_load_ushort v215, v[246:247], off offset:96
	global_load_ushort v225, v[106:107], off offset:256
	global_load_ushort v224, v[106:107], off offset:512
	global_load_ushort v217, v[106:107], off offset:768
	s_waitcnt vmcnt(0)
	ds_read_b128 v[80:83], v205
	ds_read_b128 v[84:87], v205 offset:64
	v_lshlrev_b32_e32 v103, 16, v219
	v_lshlrev_b32_e32 v102, 16, v175
	s_add_i32 s37, s37, s74
	s_waitcnt lgkmcnt(1)
	v_mfma_f32_16x16x32_bf16 v[88:91], v[24:27], v[80:83], 0
	s_add_i32 s36, s36, s74
	s_cmp_gt_i32 s37, 63
	v_mfma_f32_16x16x32_bf16 v[80:83], v[16:19], v[80:83], 0
	s_waitcnt lgkmcnt(0)
	v_mfma_f32_16x16x32_bf16 v[88:91], v[28:31], v[84:87], v[88:91]
	v_mfma_f32_16x16x32_bf16 v[80:83], v[12:15], v[84:87], v[80:83]
	ds_read_b128 v[84:87], v205 offset:128
	ds_read_b128 v[92:95], v205 offset:192
	s_waitcnt lgkmcnt(1)
	v_mfma_f32_16x16x32_bf16 v[88:91], v[36:39], v[84:87], v[88:91]
	v_mfma_f32_16x16x32_bf16 v[80:83], v[8:11], v[84:87], v[80:83]
	s_waitcnt lgkmcnt(0)
	v_mfma_f32_16x16x32_bf16 v[84:87], v[32:35], v[92:95], v[88:91]
	v_mfma_f32_16x16x32_bf16 v[80:83], v[20:23], v[92:95], v[80:83]
	s_nop 3
	ds_read_b128 v[88:91], v205 offset:4352
	ds_read_b128 v[92:95], v205 offset:4416
	s_nop 0
	v_pk_add_f32 v[84:85], v[102:103], v[84:85] neg_lo:[0,1] neg_hi:[0,1]
	v_lshlrev_b32_e32 v103, 16, v173
	s_waitcnt lgkmcnt(1)
	v_mfma_f32_16x16x32_bf16 v[98:101], v[24:27], v[88:91], 0
	v_lshlrev_b32_e32 v102, 16, v218
	v_pk_add_f32 v[86:87], v[102:103], v[86:87] neg_lo:[0,1] neg_hi:[0,1]
	v_cvt_pk_bf16_f32 v84, v84, v85
	v_mfma_f32_16x16x32_bf16 v[88:91], v[16:19], v[88:91], 0
	v_cvt_pk_bf16_f32 v85, v86, v87
	v_lshlrev_b32_e32 v103, 16, v214
	v_lshlrev_b32_e32 v102, 16, v220
	s_waitcnt lgkmcnt(0)
; #define LAS __attribute__((address_space(3)))
; #define LDS_BARRIER() do { asm volatile("s_waitcnt lgkmcnt(0)" ::: "memory"); __builtin_amdgcn_s_barrier(); asm volatile("" ::: "memory"); } while (0)
; __device__ __forceinline__ unsigned f2bf(float f) { return pk2(f, f) & 0xffffu; }
; __device__ __forceinline__ void gdn_scan_full(const bf16* CHUNK, const float* CD, bf16* OG, LAS unsigned char* lds, int item, int tid, int wave, int lane) {
;     ...
;         for (int t = 0; t < 4; ++t)
; #pragma unroll
;             for (int s = 0; s < 4; ++s) { const bf16x8_t sf = *(const LAS bf16x8_t*)(Sb + (64 * ng + 16 * t + ql) * 136 + 32 * s + 8 * gq);
;                 wsum[t] = __builtin_amdgcn_mfma_f32_16x16x32_bf16(wf[s], sf, wsum[t], 0, 0, 0); os[t] = __builtin_amdgcn_mfma_f32_16x16x32_bf16(qf[s], sf, os[t], 0, 0, 0); }
; #pragma unroll
;         for (int t = 0; t < 4; ++t) { s16x4_t vn;
; #pragma unroll
;             for (int j = 0; j < 4; ++j) vn[j] = (short)f2bf(__uint_as_float((unsigned)uu[t * 4 + j] << 16) - wsum[t][j]);
;             *(LAS s16x4_t*)(Vn + (64 * ng + 16 * t + ql) * 72 + 16 * mt + 4 * gq) = vn; }
;         LDS_BARRIER();
	v_mfma_f32_16x16x32_bf16 v[98:101], v[28:31], v[92:95], v[98:101]
	v_mfma_f32_16x16x32_bf16 v[88:91], v[12:15], v[92:95], v[88:91]
	ds_read_b128 v[92:95], v205 offset:4480
	ds_read_b128 v[110:113], v205 offset:4544
	s_waitcnt lgkmcnt(1)
	v_mfma_f32_16x16x32_bf16 v[98:101], v[36:39], v[92:95], v[98:101]
	v_mfma_f32_16x16x32_bf16 v[88:91], v[8:11], v[92:95], v[88:91]
	s_waitcnt lgkmcnt(0)
	v_mfma_f32_16x16x32_bf16 v[92:95], v[32:35], v[110:113], v[98:101]
	v_mfma_f32_16x16x32_bf16 v[88:91], v[20:23], v[110:113], v[88:91]
	s_nop 3
	ds_read_b128 v[98:101], v205 offset:8704
	ds_read_b128 v[110:113], v205 offset:8768
	ds_read_b128 v[118:121], v205 offset:8832
	ds_read_b128 v[122:125], v205 offset:8896
	ds_read_b128 v[126:129], v206
	ds_read_b128 v[130:133], v206 offset:64
	ds_read_b128 v[134:137], v206 offset:128
	ds_read_b128 v[178:181], v206 offset:192
	s_waitcnt lgkmcnt(7)
	v_mfma_f32_16x16x32_bf16 v[114:117], v[24:27], v[98:101], 0
	ds_write_b64 v108, v[84:85] offset:34816
	v_pk_add_f32 v[94:95], v[102:103], v[94:95] neg_lo:[0,1] neg_hi:[0,1]
	v_mfma_f32_16x16x32_bf16 v[98:101], v[16:19], v[98:101], 0
	s_waitcnt lgkmcnt(4)
	v_mfma_f32_16x16x32_bf16 v[24:27], v[24:27], v[126:129], 0
	v_mfma_f32_16x16x32_bf16 v[114:117], v[28:31], v[110:113], v[114:117]
	v_mfma_f32_16x16x32_bf16 v[98:101], v[12:15], v[110:113], v[98:101]
	s_waitcnt lgkmcnt(3)
	v_mfma_f32_16x16x32_bf16 v[24:27], v[28:31], v[130:133], v[24:27]
	v_lshlrev_b32_e32 v31, 16, v216
	v_lshlrev_b32_e32 v30, 16, v222
	v_mfma_f32_16x16x32_bf16 v[110:113], v[36:39], v[118:121], v[114:117]
	v_mfma_f32_16x16x32_bf16 v[84:87], v[8:11], v[118:121], v[98:101]
	s_nop 2
	v_lshlrev_b32_e32 v99, 16, v221
	v_lshlrev_b32_e32 v98, 16, v171
	s_waitcnt lgkmcnt(2)
	v_mfma_f32_16x16x32_bf16 v[24:27], v[36:39], v[134:137], v[24:27]
	v_add_f32_e64 v92, v98, -v92
	v_add_f32_e64 v93, v99, -v93
	v_or_b32_e32 v36, 0xfc0, v141
	v_cvt_pk_bf16_f32 v92, v92, v93
	v_mfma_f32_16x16x32_bf16 v[98:101], v[32:35], v[122:125], v[110:113]
	v_cvt_pk_bf16_f32 v93, v94, v95
	ds_write_b64 v108, v[92:93] offset:37120
	v_lshlrev_b32_e32 v93, 16, v223
	v_lshlrev_b32_e32 v92, 16, v213
	s_waitcnt lgkmcnt(2)
	v_mfma_f32_16x16x32_bf16 v[24:27], v[32:35], v[178:181], v[24:27]
	s_nop 1
	v_add_f32_e64 v92, v92, -v98
	v_add_f32_e64 v93, v93, -v99
	v_pk_add_f32 v[30:31], v[30:31], v[100:101] neg_lo:[0,1] neg_hi:[0,1]
	v_cvt_pk_bf16_f32 v28, v92, v93
	v_mfma_f32_16x16x32_bf16 v[16:19], v[16:19], v[126:129], 0
	v_cvt_pk_bf16_f32 v29, v30, v31
	ds_write_b64 v108, v[28:29] offset:39424
	v_lshlrev_b32_e32 v29, 16, v225
	v_lshlrev_b32_e32 v28, 16, v215
	v_pk_add_f32 v[24:25], v[28:29], v[24:25] neg_lo:[0,1] neg_hi:[0,1]
	s_waitcnt vmcnt(17)
	v_lshlrev_b32_e32 v29, 16, v217
	v_lshlrev_b32_e32 v28, 16, v224
	v_mfma_f32_16x16x32_bf16 v[12:15], v[12:15], v[130:133], v[16:19]
	v_cvt_pk_bf16_f32 v24, v24, v25
	v_cndmask_b32_e32 v36, v199, v36, vcc
	v_lshlrev_b32_e32 v144, 12, v36
	v_pk_add_f32 v[16:17], v[28:29], v[26:27] neg_lo:[0,1] neg_hi:[0,1]
	v_mfma_f32_16x16x32_bf16 v[8:11], v[8:11], v[134:137], v[12:15]
	v_cvt_pk_bf16_f32 v25, v16, v17
	ds_write_b64 v104, v[24:25] offset:34816
	s_waitcnt lgkmcnt(0)
	s_barrier
; #define LAS __attribute__((address_space(3)))
; #define LDS_BARRIER() do { asm volatile("s_waitcnt lgkmcnt(0)" ::: "memory"); __builtin_amdgcn_s_barrier(); asm volatile("" ::: "memory"); } while (0)
; __device__ __forceinline__ unsigned f2bf(float f) { return pk2(f, f) & 0xffffu; }
; __device__ __forceinline__ void gdn_scan_full(const bf16* CHUNK, const float* CD, bf16* OG, LAS unsigned char* lds, int item, int tid, int wave, int lane) {
;     ...
; #pragma unroll
;         for (int t = 0; t < 4; ++t)
; #pragma unroll
;             for (int s = 0; s < 2; ++s) { const bf16x8_t vf = *(const LAS bf16x8_t*)(Vn + (64 * ng + 16 * t + ql) * 72 + 32 * s + 8 * gq); os[t] = __builtin_amdgcn_mfma_f32_16x16x32_bf16(inf[s], vf, os[t], 0, 0, 0); }
; #pragma unroll
;         for (int j = 0; j < 4; ++j) { const int c = n * 64 + 16 * mt + 4 * gq + j; const int tok = d ? SEQ - 1 - c : c;
; #pragma unroll
;             for (int t = 0; t < 4; ++t) og[(size_t)tok * 2048 + 16 * t] = (bf16)f2bf(os[t][j]); }
; #pragma unroll
;         for (int t = 0; t < 8; ++t) S[t] = S[t] * cdv;
; #pragma unroll
;         for (int t = 0; t < 8; ++t)
; #pragma unroll
;             for (int s = 0; s < 2; ++s) { const bf16x8_t v0 = *(const LAS bf16x8_t*)(Vn + (16 * t + ql) * 72 + 32 * s + 8 * gq); S[t] = __builtin_amdgcn_mfma_f32_16x16x32_bf16(kf[s], v0, S[t], 0, 0, 0); }
; #pragma unroll
;         for (int t = 0; t < 8; ++t) { s16x4_t p;
; #pragma unroll
;             for (int j = 0; j < 4; ++j) p[j] = (short)f2bf(S[t][j]);
;             *(LAS s16x4_t*)(Sb + (16 * t + ql) * 136 + 16 * wave + 4 * gq) = p; }
;         LDS_BARRIER();
	ds_read_b128 v[12:15], v105 offset:34816
	ds_read_b128 v[16:19], v105 offset:34880
	s_waitcnt lgkmcnt(1)
	v_mfma_f32_16x16x32_bf16 v[12:15], v[40:43], v[12:15], v[80:83]
	v_mfma_f32_16x16x32_bf16 v[84:87], v[20:23], v[122:125], v[84:87]
	v_mfma_f32_16x16x32_bf16 v[8:11], v[20:23], v[178:181], v[8:11]
	s_waitcnt lgkmcnt(0)
	v_mfma_f32_16x16x32_bf16 v[12:15], v[44:47], v[16:19], v[12:15]
	ds_read_b128 v[16:19], v105 offset:37120
	ds_read_b128 v[20:23], v105 offset:37184
	ds_read_b128 v[24:27], v105 offset:39424
	ds_read_b128 v[28:31], v105 offset:39488
	s_waitcnt lgkmcnt(3)
	v_mfma_f32_16x16x32_bf16 v[16:19], v[40:43], v[16:19], v[88:91]
	s_nop 1
	v_cvt_pk_bf16_f32 v12, v12, s0
	s_waitcnt lgkmcnt(2)
	v_mfma_f32_16x16x32_bf16 v[16:19], v[44:47], v[20:23], v[16:19]
	ds_read_b128 v[20:23], v96 offset:34816
	ds_read_b128 v[32:35], v96 offset:34880
	ds_read_b128 v[36:39], v207 offset:39488
	s_waitcnt lgkmcnt(2)
	v_mfma_f32_16x16x32_bf16 v[8:11], v[40:43], v[20:23], v[8:11]
	ds_read_b128 v[20:23], v207 offset:34880
	v_mfma_f32_16x16x32_bf16 v[24:27], v[40:43], v[24:27], v[84:87]
	ds_read_b128 v[40:43], v208 offset:34816
	s_waitcnt lgkmcnt(3)
	v_mfma_f32_16x16x32_bf16 v[8:11], v[44:47], v[32:35], v[8:11]
	ds_read_b128 v[32:35], v207 offset:39424
	v_mfma_f32_16x16x32_bf16 v[24:27], v[44:47], v[28:31], v[24:27]
	v_lshl_add_u64 v[28:29], v[192:193], 0, v[144:145]
	s_nop 4
	v_cvt_pk_bf16_f32 v8, v8, s0
	global_store_short v[28:29], v8, off offset:96
	v_or_b32_e32 v8, 0xfc1, v141
	global_store_short v[28:29], v12, off
	v_cvt_pk_bf16_f32 v12, v16, s0
	v_cndmask_b32_e32 v8, v200, v8, vcc
	global_store_short v[28:29], v12, off offset:32
	v_cvt_pk_bf16_f32 v12, v24, s0
	v_lshlrev_b32_e32 v144, 12, v8
	global_store_short v[28:29], v12, off offset:64
	v_cvt_pk_bf16_f32 v16, v13, s0
	v_lshl_add_u64 v[12:13], v[192:193], 0, v[144:145]
	v_cvt_pk_bf16_f32 v8, v17, s0
	global_store_short v[12:13], v8, off offset:32
	v_cvt_pk_bf16_f32 v8, v25, s0
	global_store_short v[12:13], v8, off offset:64
	v_cvt_pk_bf16_f32 v8, v9, s0
	global_store_short v[12:13], v8, off offset:96
	v_or_b32_e32 v8, 0xfc2, v141
	v_cndmask_b32_e32 v8, v201, v8, vcc
	v_lshlrev_b32_e32 v144, 12, v8
	global_store_short v[12:13], v16, off
	v_cvt_pk_bf16_f32 v12, v14, s0
	v_lshl_add_u64 v[8:9], v[192:193], 0, v[144:145]
	global_store_short v[8:9], v12, off
	v_cvt_pk_bf16_f32 v12, v18, s0
	global_store_short v[8:9], v12, off offset:32
	v_cvt_pk_bf16_f32 v12, v26, s0
	v_cvt_pk_bf16_f32 v10, v10, s0
	global_store_short v[8:9], v12, off offset:64
	global_store_short v[8:9], v10, off offset:96
	v_or_b32_e32 v8, 0xfc3, v141
	v_cndmask_b32_e32 v8, v202, v8, vcc
	v_lshlrev_b32_e32 v144, 12, v8
	v_cvt_pk_bf16_f32 v10, v15, s0
	v_lshl_add_u64 v[8:9], v[192:193], 0, v[144:145]
	global_store_short v[8:9], v10, off
	v_cvt_pk_bf16_f32 v10, v19, s0
	global_store_short v[8:9], v10, off offset:32
	v_cvt_pk_bf16_f32 v10, v27, s0
	ds_read_b128 v[12:15], v207 offset:34816
	ds_read_b128 v[24:27], v207 offset:37120
	ds_read_b128 v[28:31], v207 offset:37184
	global_store_short v[8:9], v10, off offset:64
	v_cvt_pk_bf16_f32 v10, v11, s0
	global_store_short v[8:9], v10, off offset:96
	s_waitcnt vmcnt(32)
	v_pk_mul_f32 v[10:11], v[194:195], v[74:75] op_sel_hi:[0,1]
	v_pk_mul_f32 v[8:9], v[194:195], v[72:73] op_sel_hi:[0,1]
	v_pk_mul_f32 v[18:19], v[194:195], v[78:79] op_sel_hi:[0,1]
	v_pk_mul_f32 v[16:17], v[194:195], v[76:77] op_sel_hi:[0,1]
	s_waitcnt lgkmcnt(2)
	v_mfma_f32_16x16x32_bf16 v[8:11], v[4:7], v[12:15], v[8:11]
	v_mul_f32_e64 v14, v194, v70
	v_mul_f32_e64 v15, v194, v71
	v_pk_mul_f32 v[12:13], v[194:195], v[68:69] op_sel_hi:[0,1]
	ds_read_b128 v[44:47], v208 offset:34880
	s_waitcnt lgkmcnt(2)
	v_mfma_f32_16x16x32_bf16 v[16:19], v[4:7], v[24:27], v[16:19]
	v_mul_f32_e64 v26, v194, v62
	v_mul_f32_e64 v27, v194, v63
	v_pk_mul_f32 v[24:25], v[194:195], v[60:61] op_sel_hi:[0,1]
	v_mfma_f32_16x16x32_bf16 v[12:15], v[4:7], v[32:35], v[12:15]
	v_mul_f32_e64 v34, v194, v54
	v_mul_f32_e64 v35, v194, v55
	v_pk_mul_f32 v[32:33], v[194:195], v[52:53] op_sel_hi:[0,1]
	v_mfma_f32_16x16x32_bf16 v[8:11], v[0:3], v[20:23], v[8:11]
	v_mul_f32_e64 v22, v194, v66
	v_mul_f32_e64 v23, v194, v67
	v_pk_mul_f32 v[20:21], v[194:195], v[64:65] op_sel_hi:[0,1]
	s_waitcnt lgkmcnt(1)
	v_mfma_f32_16x16x32_bf16 v[16:19], v[0:3], v[28:31], v[16:19]
	v_mul_f32_e64 v30, v194, v58
	v_mul_f32_e64 v31, v194, v59
	v_pk_mul_f32 v[28:29], v[194:195], v[56:57] op_sel_hi:[0,1]
	v_cvt_pk_bf16_f32 v11, v10, v11
	v_mfma_f32_16x16x32_bf16 v[12:15], v[0:3], v[36:39], v[12:15]
	v_mul_f32_e64 v38, v194, v50
	v_mul_f32_e64 v39, v194, v51
	v_pk_mul_f32 v[36:37], v[194:195], v[48:49] op_sel_hi:[0,1]
	v_cvt_pk_bf16_f32 v19, v18, v19
	v_mfma_f32_16x16x32_bf16 v[20:23], v[4:7], v[40:43], v[20:23]
	ds_read_b128 v[40:43], v207 offset:44032
	ds_read_b128 v[48:51], v207 offset:44096
	ds_read_b128 v[52:55], v207 offset:46336
	ds_read_b128 v[56:59], v207 offset:46400
	v_cvt_pk_bf16_f32 v18, v16, v17
	v_cvt_pk_bf16_f32 v10, v8, v9
	s_waitcnt lgkmcnt(4)
	v_mfma_f32_16x16x32_bf16 v[20:23], v[0:3], v[44:47], v[20:23]
	ds_read_b128 v[44:47], v207 offset:48640
	ds_read_b128 v[60:63], v207 offset:48704
	ds_read_b128 v[64:67], v209 offset:34816
	ds_read_b128 v[68:71], v209 offset:34880
	ds_write_b64 v210, v[18:19] offset:4352
	v_cvt_pk_bf16_f32 v15, v14, v15
	s_waitcnt lgkmcnt(8)
	v_mfma_f32_16x16x32_bf16 v[24:27], v[4:7], v[40:43], v[24:27]
	v_cvt_pk_bf16_f32 v14, v12, v13
	ds_write_b64 v210, v[10:11]
	ds_write_b64 v210, v[14:15] offset:8704
	s_waitcnt lgkmcnt(8)
	v_mfma_f32_16x16x32_bf16 v[16:19], v[4:7], v[52:55], v[28:31]
	v_mfma_f32_16x16x32_bf16 v[8:11], v[0:3], v[48:51], v[24:27]
	s_waitcnt lgkmcnt(7)
	v_mfma_f32_16x16x32_bf16 v[12:15], v[0:3], v[56:59], v[16:19]
	s_nop 4
	v_cvt_pk_bf16_f32 v17, v22, v23
	v_cvt_pk_bf16_f32 v16, v20, v21
	ds_write_b64 v211, v[16:17]
	s_waitcnt lgkmcnt(7)
	v_mfma_f32_16x16x32_bf16 v[16:19], v[4:7], v[44:47], v[32:35]
	v_cvt_pk_bf16_f32 v11, v10, v11
	v_cvt_pk_bf16_f32 v10, v8, v9
	ds_write_b64 v210, v[10:11] offset:17408
	s_waitcnt lgkmcnt(6)
	v_mfma_f32_16x16x32_bf16 v[4:7], v[4:7], v[64:67], v[36:39]
	v_cvt_pk_bf16_f32 v15, v14, v15
	v_cvt_pk_bf16_f32 v14, v12, v13
	ds_write_b64 v210, v[14:15] offset:21760
	v_mfma_f32_16x16x32_bf16 v[8:11], v[0:3], v[60:63], v[16:19]
	s_waitcnt lgkmcnt(6)
	v_mfma_f32_16x16x32_bf16 v[0:3], v[0:3], v[68:71], v[4:7]
	s_nop 5
	v_cvt_pk_bf16_f32 v11, v10, v11
	v_cvt_pk_bf16_f32 v10, v8, v9
	v_cvt_pk_bf16_f32 v3, v2, v3
	v_cvt_pk_bf16_f32 v2, v0, v1
	ds_write_b64 v210, v[10:11] offset:26112
	ds_write_b64 v212, v[2:3]
	s_waitcnt lgkmcnt(0)
	s_barrier
	s_waitcnt lgkmcnt(0)
	s_barrier
	s_cbranch_scc0 .LBB0_364

; __global__ void __launch_bounds__(NTHR) fwd(Args args) {
	.amdhsa_kernel _Z3fwd4Args
		.amdhsa_group_segment_fixed_size 0
		.amdhsa_private_segment_fixed_size 0
		.amdhsa_kernarg_size 416
		.amdhsa_user_sgpr_count 2
		.amdhsa_user_sgpr_dispatch_ptr 0
		.amdhsa_user_sgpr_queue_ptr 0
		.amdhsa_user_sgpr_kernarg_segment_ptr 1
		.amdhsa_user_sgpr_dispatch_id 0
		.amdhsa_user_sgpr_kernarg_preload_length 0
		.amdhsa_user_sgpr_kernarg_preload_offset 0
		.amdhsa_user_sgpr_private_segment_size 0
		.amdhsa_uses_dynamic_stack 0
		.amdhsa_enable_private_segment 0
		.amdhsa_system_sgpr_workgroup_id_x 1
		.amdhsa_system_sgpr_workgroup_id_y 0
		.amdhsa_system_sgpr_workgroup_id_z 0
		.amdhsa_system_sgpr_workgroup_info 0
		.amdhsa_system_vgpr_workitem_id 2
		.amdhsa_next_free_vgpr 254
		.amdhsa_next_free_sgpr 102
		.amdhsa_accum_offset 256
		.amdhsa_reserve_vcc 1
		.amdhsa_float_round_mode_32 0
		.amdhsa_float_round_mode_16_64 0
		.amdhsa_float_denorm_mode_32 3
		.amdhsa_float_denorm_mode_16_64 3
		.amdhsa_dx10_clamp 1
		.amdhsa_ieee_mode 1
		.amdhsa_fp16_overflow 0
		.amdhsa_tg_split 0
		.amdhsa_exception_fp_ieee_invalid_op 0
		.amdhsa_exception_fp_denorm_src 0
		.amdhsa_exception_fp_ieee_div_zero 0
		.amdhsa_exception_fp_ieee_overflow 0
		.amdhsa_exception_fp_ieee_underflow 0
		.amdhsa_exception_fp_ieee_inexact 0
		.amdhsa_exception_int_div_zero 0
	.end_amdhsa_kernel

; __global__ void __launch_bounds__(NTHR) fwd(Args args) {
amdhsa.kernels:
  - .agpr_count:     0
    .args:
      - .offset:         0
        .size:           160
        .value_kind:     by_value
      - .offset:         160
        .size:           4
        .value_kind:     hidden_block_count_x
      - .offset:         164
        .size:           4
        .value_kind:     hidden_block_count_y
      - .offset:         168
        .size:           4
        .value_kind:     hidden_block_count_z
      - .offset:         172
        .size:           2
        .value_kind:     hidden_group_size_x
      - .offset:         174
        .size:           2
        .value_kind:     hidden_group_size_y
      - .offset:         176
        .size:           2
        .value_kind:     hidden_group_size_z
      - .offset:         178
        .size:           2
        .value_kind:     hidden_remainder_x
      - .offset:         180
        .size:           2
        .value_kind:     hidden_remainder_y
      - .offset:         182
        .size:           2
        .value_kind:     hidden_remainder_z
      - .offset:         200
        .size:           8
        .value_kind:     hidden_global_offset_x
      - .offset:         208
        .size:           8
        .value_kind:     hidden_global_offset_y
      - .offset:         216
        .size:           8
        .value_kind:     hidden_global_offset_z
      - .offset:         224
        .size:           2
        .value_kind:     hidden_grid_dims
      - .offset:         248
        .size:           8
        .value_kind:     hidden_multigrid_sync_arg
      - .offset:         280
        .size:           4
        .value_kind:     hidden_dynamic_lds_size
    .group_segment_fixed_size: 0
    .kernarg_segment_align: 8
    .kernarg_segment_size: 416
    .language:       OpenCL C
    .language_version:
      - 2
      - 0
    .max_flat_workgroup_size: 512
    .name:           _Z3fwd4Args
    .private_segment_fixed_size: 0
    .sgpr_count:     108
    .sgpr_spill_count: 54
    .symbol:         _Z3fwd4Args.kd
    .uniform_work_group_size: 1
    .uses_dynamic_stack: false
    .vgpr_count:     254
    .vgpr_spill_count: 0
    .wavefront_size: 64
